# GEMM prologues: K-tile 1 staging issued before the wait/barrier that retires K-tile 0 (one memory round trip per GEMM phase instead of two)
# speedup vs baseline: 1.0019x; 1.0019x over previous
.LBB0_92:
	s_lshl_b32 s18, s18, 5
	s_and_b32 s30, s18, 0x60
	s_add_i32 m0, s22, 0x18000
	v_lshl_add_u64 v[6:7], v[6:7], 0, s[10:11]
	s_lshl_b32 s28, s17, 13
	s_lshl_b32 s31, s30, 7
	global_load_lds_dwordx4 v[6:7], off
	v_lshl_add_u64 v[4:5], v[4:5], 0, s[10:11]
	s_add_i32 m0, s22, 0x1a000
	s_add_i32 s26, s22, 0x8000
	s_add_i32 s27, s22, 0xa000
	global_load_lds_dwordx4 v[4:5], off
	v_lshl_add_u64 v[0:1], v[0:1], 0, s[10:11]
	s_mov_b32 m0, s26
	s_add_u32 s18, s50, 0x40080
	global_load_lds_dwordx4 v[0:1], off
	v_lshl_add_u64 v[0:1], v[2:3], 0, s[10:11]
	s_mov_b32 m0, s27
	s_addc_u32 s19, s51, 0
	global_load_lds_dwordx4 v[0:1], off
	s_add_i32 m0, s22, 0x1c000
	v_lshl_add_u64 v[0:1], s[18:19], 0, v[196:197]
	global_load_lds_dwordx4 v[0:1], off
	v_lshl_add_u64 v[0:1], s[18:19], 0, v[128:129]
	s_add_i32 m0, s22, 0x1e000
	s_cmpk_lt_u32 s16, 0x100
	global_load_lds_dwordx4 v[0:1], off
	s_waitcnt vmcnt(8)
	s_barrier
	v_lshrrev_b32_e32 v1, 1, v9
	v_and_b32_e32 v1, 24, v1
	v_and_b32_e32 v0, 15, v9
	v_lshlrev_b32_e32 v2, 1, v1
	v_lshl_or_b32 v139, s17, 6, v0
	v_lshl_or_b32 v0, v0, 6, v2
	v_lshlrev_b32_e32 v2, 2, v9
	v_and_b32_e32 v2, 32, v2
	v_bitop3_b32 v3, v0, s28, v2 bitop3:0xde
	v_bitop3_b32 v140, v0, s31, v2 bitop3:0xde
	v_lshlrev_b32_e32 v0, 14, v13
	v_and_b32_e32 v0, 0xffff8000, v0
	v_or_b32_e32 v141, s30, v1
	v_lshl_add_u32 v0, v12, 11, v0
	v_and_b32_e32 v1, 1, v13
	v_lshl_or_b32 v0, v1, 6, v0
	v_lshl_add_u32 v134, v14, 1, v0
	v_lshlrev_b32_e32 v0, 14, v8
	v_and_b32_e32 v0, 0xffff8000, v0
	s_waitcnt vmcnt(6)
	v_lshl_add_u32 v0, v10, 11, v0
	v_and_b32_e32 v1, 1, v8
	v_lshl_or_b32 v0, v1, 6, v0
	s_sext_i32_i8 s29, s4
	s_cselect_b64 s[16:17], -1, 0
	s_ashr_i32 s4, s8, 31
	v_mov_b32_e32 v135, v197
	v_lshl_add_u32 v136, v11, 1, v0
	v_mov_b32_e32 v137, v197
	s_mov_b32 s28, 0
	v_add_u32_e32 v142, 0, v3
	s_barrier
	s_branch .LBB0_95

.LBB0_693:
	v_and_b32_e32 v143, 15, v142
	v_and_b32_e32 v14, 48, v142
	v_lshlrev_b32_e32 v15, 2, v142
	v_lshl_add_u64 v[6:7], s[46:47], 0, v[196:197]
	v_mov_b32_e32 v133, v197
	s_and_b32 s26, s2, 3
	s_lshl_b32 s30, s12, 6
	s_lshl_b32 s12, s12, 13
	v_lshl_or_b32 v14, v143, 6, v14
	v_and_b32_e32 v15, 32, v15
	v_lshl_add_u64 v[8:9], s[46:47], 0, v[132:133]
	v_mov_b32_e32 v129, v197
	v_bitop3_b32 v16, v14, s12, v15 bitop3:0xde
	s_lshl_b32 s12, s26, 12
	s_add_i32 m0, s9, 0x18000
	v_lshl_add_u64 v[6:7], v[6:7], 0, s[10:11]
	v_lshl_add_u64 v[10:11], s[14:15], 0, v[128:129]
	v_mov_b32_e32 v131, v197
	v_bitop3_b32 v144, v14, s12, v15 bitop3:0xde
	s_sext_i32_i8 s12, s4
	global_load_lds_dwordx4 v[6:7], off
	v_lshl_add_u64 v[6:7], v[8:9], 0, s[10:11]
	s_add_i32 m0, s9, 0x1a000
	s_add_i32 s4, s9, 0x8000
	s_add_i32 s31, s9, 0xa000
	v_lshl_add_u64 v[12:13], s[14:15], 0, v[130:131]
	global_load_lds_dwordx4 v[6:7], off
	v_lshl_add_u64 v[6:7], v[10:11], 0, s[10:11]
	s_mov_b32 m0, s4
	s_add_u32 s16, s46, 0x40080
	global_load_lds_dwordx4 v[6:7], off
	v_lshl_add_u64 v[6:7], v[12:13], 0, s[10:11]
	s_mov_b32 m0, s31
	s_addc_u32 s17, s47, 0
	global_load_lds_dwordx4 v[6:7], off
	s_add_i32 m0, s9, 0x1c000
	v_lshl_add_u64 v[6:7], s[16:17], 0, v[196:197]
	global_load_lds_dwordx4 v[6:7], off
	v_lshl_add_u64 v[6:7], s[16:17], 0, v[132:133]
	s_add_i32 m0, s9, 0x1e000
	v_add_u32_e32 v145, 0, v16
	global_load_lds_dwordx4 v[6:7], off
	s_waitcnt vmcnt(8)
	s_barrier
	v_lshlrev_b32_e32 v6, 14, v0
	v_and_b32_e32 v6, 0xffff8000, v6
	v_lshl_add_u32 v1, v1, 11, v6
	v_and_b32_e32 v0, 1, v0
	v_lshl_or_b32 v0, v0, 6, v1
	v_lshl_add_u32 v134, v2, 1, v0
	v_lshlrev_b32_e32 v0, 14, v3
	v_and_b32_e32 v0, 0xffff8000, v0
	v_lshl_add_u32 v0, v4, 11, v0
	v_and_b32_e32 v1, 1, v3
	s_waitcnt vmcnt(6)
	v_lshl_or_b32 v0, v1, 6, v0
	v_mov_b32_e32 v2, v197
	v_mov_b32_e32 v3, v197
	v_lshl_add_u32 v136, v5, 1, v0
	v_mov_b32_e32 v0, v197
	v_mov_b32_e32 v1, v197
	v_mov_b64_e32 v[6:7], v[2:3]
	v_mov_b64_e32 v[18:19], v[2:3]
	v_mov_b64_e32 v[22:23], v[2:3]
	v_mov_b64_e32 v[34:35], v[2:3]
	v_mov_b64_e32 v[38:39], v[2:3]
	v_mov_b64_e32 v[50:51], v[2:3]
	s_waitcnt vmcnt(0)
	v_mov_b64_e32 v[54:55], v[2:3]
	v_mov_b64_e32 v[10:11], v[2:3]
	v_mov_b64_e32 v[14:15], v[2:3]
	v_mov_b64_e32 v[26:27], v[2:3]
	v_mov_b64_e32 v[30:31], v[2:3]
	v_mov_b64_e32 v[42:43], v[2:3]
	v_mov_b64_e32 v[46:47], v[2:3]
	v_mov_b64_e32 v[58:59], v[2:3]
	v_mov_b64_e32 v[62:63], v[2:3]
	v_mov_b64_e32 v[106:107], v[2:3]
	v_mov_b64_e32 v[118:119], v[2:3]
	v_mov_b64_e32 v[82:83], v[2:3]
	v_mov_b64_e32 v[86:87], v[2:3]
	v_mov_b64_e32 v[126:127], v[2:3]
	v_mov_b64_e32 v[122:123], v[2:3]
	v_mov_b64_e32 v[102:103], v[2:3]
	v_mov_b64_e32 v[98:99], v[2:3]
	v_mov_b64_e32 v[90:91], v[2:3]
	v_mov_b64_e32 v[94:95], v[2:3]
	v_mov_b64_e32 v[74:75], v[2:3]
	v_mov_b64_e32 v[78:79], v[2:3]
	v_mov_b64_e32 v[110:111], v[2:3]
	v_mov_b64_e32 v[114:115], v[2:3]
	v_mov_b64_e32 v[66:67], v[2:3]
	v_mov_b64_e32 v[70:71], v[2:3]
	v_or_b32_e32 v146, s30, v143
	v_mov_b32_e32 v135, v197
	v_mov_b32_e32 v137, v197
	s_mov_b32 s34, 0
	v_mov_b64_e32 v[4:5], v[0:1]
	v_mov_b64_e32 v[16:17], v[0:1]
	v_mov_b64_e32 v[20:21], v[0:1]
	v_mov_b64_e32 v[32:33], v[0:1]
	v_mov_b64_e32 v[36:37], v[0:1]
	v_mov_b64_e32 v[48:49], v[0:1]
	v_mov_b64_e32 v[52:53], v[0:1]
	v_mov_b64_e32 v[8:9], v[0:1]
	v_mov_b64_e32 v[12:13], v[0:1]
	v_mov_b64_e32 v[24:25], v[0:1]
	v_mov_b64_e32 v[28:29], v[0:1]
	v_mov_b64_e32 v[40:41], v[0:1]
	v_mov_b64_e32 v[44:45], v[0:1]
	v_mov_b64_e32 v[56:57], v[0:1]
	v_mov_b64_e32 v[60:61], v[0:1]
	v_mov_b64_e32 v[104:105], v[0:1]
	v_mov_b64_e32 v[116:117], v[0:1]
	v_mov_b64_e32 v[80:81], v[0:1]
	v_mov_b64_e32 v[84:85], v[0:1]
	v_mov_b64_e32 v[124:125], v[0:1]
	v_mov_b64_e32 v[120:121], v[0:1]
	v_mov_b64_e32 v[100:101], v[0:1]
	v_mov_b64_e32 v[96:97], v[0:1]
	v_mov_b64_e32 v[88:89], v[0:1]
	v_mov_b64_e32 v[92:93], v[0:1]
	v_mov_b64_e32 v[72:73], v[0:1]
	v_mov_b64_e32 v[76:77], v[0:1]
	v_mov_b64_e32 v[108:109], v[0:1]
	v_mov_b64_e32 v[112:113], v[0:1]
	v_mov_b64_e32 v[64:65], v[0:1]
	v_mov_b64_e32 v[68:69], v[0:1]
	s_barrier

.LBB0_793:
	v_lshrrev_b32_e32 v16, 1, v14
	v_and_b32_e32 v16, 24, v16
	s_add_u32 s12, s6, 0x3e00000
	v_and_b32_e32 v15, 15, v14
	v_lshlrev_b32_e32 v17, 1, v16
	v_lshlrev_b32_e32 v14, 2, v14
	s_sext_i32_i16 s31, s4
	s_addc_u32 s13, s7, 0
	v_lshl_or_b32 v138, s16, 6, v15
	v_lshl_or_b32 v15, v15, 6, v17
	s_lshl_b32 s4, s16, 13
	v_and_b32_e32 v14, 32, v14
	v_bitop3_b32 v17, v15, s4, v14 bitop3:0xde
	s_lshl_b32 s4, s15, 5
	s_and_b32 s18, s4, 0x60
	s_lshl_b32 s4, s18, 7
	s_add_i32 m0, s24, 0x18000
	v_lshl_add_u64 v[6:7], v[6:7], 0, s[10:11]
	v_bitop3_b32 v139, v15, s4, v14 bitop3:0xde
	global_load_lds_dwordx4 v[6:7], off
	v_lshl_add_u64 v[4:5], v[4:5], 0, s[10:11]
	s_add_i32 m0, s24, 0x1a000
	s_add_i32 s4, s24, 0x8000
	s_add_i32 s28, s24, 0xa000
	global_load_lds_dwordx4 v[4:5], off
	v_lshl_add_u64 v[0:1], v[0:1], 0, s[10:11]
	s_mov_b32 m0, s4
	s_add_u32 s16, s48, 0x40080
	global_load_lds_dwordx4 v[0:1], off
	v_lshl_add_u64 v[0:1], v[2:3], 0, s[10:11]
	s_mov_b32 m0, s28
	s_addc_u32 s17, s49, 0
	global_load_lds_dwordx4 v[0:1], off
	s_add_i32 m0, s24, 0x1c000
	v_lshl_add_u64 v[0:1], s[16:17], 0, v[196:197]
	global_load_lds_dwordx4 v[0:1], off
	v_lshl_add_u64 v[0:1], s[16:17], 0, v[128:129]
	s_add_i32 m0, s24, 0x1e000
	s_cmpk_lt_u32 s14, 0x100
	global_load_lds_dwordx4 v[0:1], off
	s_waitcnt vmcnt(8)
	s_barrier
	v_lshlrev_b32_e32 v0, 14, v12
	v_and_b32_e32 v0, 0xffff8000, v0
	v_lshl_add_u32 v0, v11, 11, v0
	v_and_b32_e32 v1, 1, v12
	v_lshl_or_b32 v0, v1, 6, v0
	v_lshl_add_u32 v134, v13, 1, v0
	v_lshlrev_b32_e32 v0, 14, v8
	v_and_b32_e32 v0, 0xffff8000, v0
	s_waitcnt vmcnt(6)
	v_lshl_add_u32 v0, v9, 11, v0
	v_and_b32_e32 v1, 1, v8
	v_lshl_or_b32 v0, v1, 6, v0
	s_cselect_b64 s[14:15], -1, 0
	s_ashr_i32 s29, s0, 31
	v_or_b32_e32 v140, s18, v16
	v_mov_b32_e32 v135, v197
	v_lshl_add_u32 v136, v10, 1, v0
	v_mov_b32_e32 v137, v197
	s_mov_b32 s30, 0
	v_add_u32_e32 v141, 0, v17
	s_barrier
	s_waitcnt vmcnt(0)
	s_branch .LBB0_796

.LBB0_813:
	v_lshrrev_b32_e32 v10, 1, v8
	s_sub_i32 s0, s0, s14
	v_and_b32_e32 v10, 24, v10
	s_add_u32 s6, s6, 0xdb00000
	v_and_b32_e32 v9, 15, v8
	v_lshlrev_b32_e32 v11, 1, v10
	v_lshlrev_b32_e32 v8, 2, v8
	s_sext_i32_i8 s31, s4
	s_addc_u32 s7, s7, 0
	v_lshl_or_b32 v136, s15, 6, v9
	v_lshl_or_b32 v9, v9, 6, v11
	s_lshl_b32 s4, s15, 13
	v_and_b32_e32 v8, 32, v8
	v_bitop3_b32 v11, v9, s4, v8 bitop3:0xde
	s_lshl_b32 s4, s13, 5
	s_and_b32 s16, s4, 0x60
	s_lshl_b32 s4, s16, 7
	s_add_i32 m0, s24, 0x18000
	v_lshl_add_u64 v[6:7], v[6:7], 0, s[10:11]
	v_bitop3_b32 v137, v9, s4, v8 bitop3:0xde
	global_load_lds_dwordx4 v[6:7], off
	v_lshl_add_u64 v[4:5], v[4:5], 0, s[10:11]
	s_add_i32 m0, s24, 0x1a000
	s_add_i32 s4, s24, 0x8000
	s_add_i32 s28, s24, 0xa000
	global_load_lds_dwordx4 v[4:5], off
	v_lshl_add_u64 v[0:1], v[0:1], 0, s[10:11]
	s_mov_b32 m0, s4
	s_add_u32 s14, s44, 0x10080
	global_load_lds_dwordx4 v[0:1], off
	v_lshl_add_u64 v[0:1], v[2:3], 0, s[10:11]
	s_mov_b32 m0, s28
	s_addc_u32 s15, s45, 0
	global_load_lds_dwordx4 v[0:1], off
	s_add_i32 m0, s24, 0x1c000
	v_lshl_add_u64 v[0:1], s[14:15], 0, v[196:197]
	global_load_lds_dwordx4 v[0:1], off
	v_lshl_add_u64 v[0:1], s[14:15], 0, v[132:133]
	s_add_i32 m0, s24, 0x1e000
	s_cmpk_lt_u32 s12, 0x100
	global_load_lds_dwordx4 v[0:1], off
	s_waitcnt vmcnt(8)
	s_barrier
	s_waitcnt vmcnt(6)
	s_cselect_b64 s[12:13], -1, 0
	s_ashr_i32 s29, s0, 31
	v_or_b32_e32 v138, s16, v10
	s_mov_b32 s30, 0
	v_add_u32_e32 v139, 0, v11
	s_barrier
	s_waitcnt vmcnt(0)
	s_branch .LBB0_816

.LBB0_889:
	s_add_u32 s8, s8, 0x1e00000
	s_addc_u32 s9, s9, 0
	s_lshl_b32 s15, s15, 5
	s_and_b32 s15, s15, 0x60
	s_add_i32 m0, s23, 0x18000
	v_lshl_add_u64 v[6:7], v[6:7], 0, s[10:11]
	s_lshl_b32 s29, s13, 13
	s_lshl_b32 s30, s15, 7
	global_load_lds_dwordx4 v[6:7], off
	v_lshl_add_u64 v[4:5], v[4:5], 0, s[10:11]
	s_add_i32 m0, s23, 0x1a000
	s_add_i32 s27, s23, 0x8000
	s_add_i32 s28, s23, 0xa000
	global_load_lds_dwordx4 v[4:5], off
	v_lshl_add_u64 v[0:1], v[0:1], 0, s[10:11]
	s_mov_b32 m0, s27
	s_add_u32 s16, s42, 0xb0080
	global_load_lds_dwordx4 v[0:1], off
	v_lshl_add_u64 v[0:1], v[2:3], 0, s[10:11]
	s_mov_b32 m0, s28
	s_addc_u32 s17, s43, 0
	global_load_lds_dwordx4 v[0:1], off
	s_add_i32 m0, s23, 0x1c000
	v_lshl_add_u64 v[0:1], s[16:17], 0, v[196:197]
	global_load_lds_dwordx4 v[0:1], off
	v_lshl_add_u64 v[0:1], s[16:17], 0, v[132:133]
	s_add_i32 m0, s23, 0x1e000
	s_movk_i32 s16, 0xb00
	global_load_lds_dwordx4 v[0:1], off
	s_waitcnt vmcnt(8)
	s_barrier
	v_lshrrev_b32_e32 v1, 1, v8
	v_and_b32_e32 v1, 24, v1
	v_and_b32_e32 v0, 15, v8
	v_lshlrev_b32_e32 v2, 1, v1
	v_lshl_or_b32 v142, s13, 6, v0
	v_lshl_or_b32 v0, v0, 6, v2
	v_lshlrev_b32_e32 v2, 2, v8
	v_and_b32_e32 v2, 32, v2
	v_bitop3_b32 v3, v0, s29, v2 bitop3:0xde
	v_bitop3_b32 v143, v0, s30, v2 bitop3:0xde
	v_or_b32_e32 v144, s15, v1
	v_lshrrev_b32_e32 v1, 1, v9
	v_mul_lo_u32 v0, v11, s16
	s_mov_b32 s17, 0xb000
	s_sext_i32_i8 s36, s14
	v_mad_u64_u32 v[0:1], s[14:15], v1, s17, v[0:1]
	v_or_b32_e32 v0, v0, v10
	v_add_lshl_u32 v0, v0, v12, 1
	v_mov_b32_e32 v1, v197
	s_mov_b64 s[30:31], 0xb0080
	v_lshl_add_u64 v[134:135], v[0:1], 0, s[30:31]
	v_lshrrev_b32_e32 v1, 1, v13
	v_mul_lo_u32 v0, v15, s16
	v_mad_u64_u32 v[0:1], s[14:15], v1, s17, v[0:1]
	s_waitcnt vmcnt(6)
	v_or_b32_e32 v0, v0, v14
	s_cmpk_lt_u32 s12, 0x100
	v_add_lshl_u32 v0, v0, v16, 1
	v_mov_b32_e32 v1, v197
	s_cselect_b64 s[12:13], -1, 0
	s_ashr_i32 s29, s0, 31
	v_lshl_add_u64 v[136:137], v[0:1], 0, s[30:31]
	s_mov_b32 s30, 0
	v_add_u32_e32 v145, 0, v3
	s_barrier
	s_branch .LBB0_892

.LBB0_970:
	v_lshl_add_u64 v[6:7], s[48:49], 0, v[196:197]
	v_mov_b32_e32 v133, v197
	v_and_b32_e32 v142, 15, v155
	v_and_b32_e32 v14, 48, v155
	v_lshlrev_b32_e32 v15, 2, v155
	v_lshl_add_u64 v[8:9], s[48:49], 0, v[132:133]
	v_mov_b32_e32 v129, v197
	s_sext_i32_i8 s42, s4
	s_and_b32 s3, s43, 3
	s_lshl_b32 s4, s8, 6
	s_lshl_b32 s8, s8, 13
	v_lshl_or_b32 v14, v142, 6, v14
	v_and_b32_e32 v15, 32, v15
	s_add_i32 m0, s2, 0x18000
	v_lshl_add_u64 v[6:7], v[6:7], 0, s[10:11]
	v_lshl_add_u64 v[10:11], s[6:7], 0, v[128:129]
	v_mov_b32_e32 v131, v197
	v_bitop3_b32 v16, v14, s8, v15 bitop3:0xde
	s_lshl_b32 s8, s3, 12
	global_load_lds_dwordx4 v[6:7], off
	v_lshl_add_u64 v[6:7], v[8:9], 0, s[10:11]
	s_add_i32 m0, s2, 0x1a000
	s_add_i32 s22, s2, 0x8000
	s_add_i32 s23, s2, 0xa000
	v_lshl_add_u64 v[12:13], s[6:7], 0, v[130:131]
	v_bitop3_b32 v143, v14, s8, v15 bitop3:0xde
	global_load_lds_dwordx4 v[6:7], off
	v_lshl_add_u64 v[6:7], v[10:11], 0, s[10:11]
	s_mov_b32 m0, s22
	s_add_u32 s8, s48, 0x40080
	global_load_lds_dwordx4 v[6:7], off
	v_lshl_add_u64 v[6:7], v[12:13], 0, s[10:11]
	s_mov_b32 m0, s23
	s_addc_u32 s9, s49, 0
	global_load_lds_dwordx4 v[6:7], off
	s_add_i32 m0, s2, 0x1c000
	v_lshl_add_u64 v[6:7], s[8:9], 0, v[196:197]
	global_load_lds_dwordx4 v[6:7], off
	v_lshl_add_u64 v[6:7], s[8:9], 0, v[132:133]
	s_add_i32 m0, s2, 0x1e000
	v_or_b32_e32 v154, s4, v142
	global_load_lds_dwordx4 v[6:7], off
	s_waitcnt vmcnt(8)
	s_barrier
	v_lshlrev_b32_e32 v6, 14, v0
	v_and_b32_e32 v6, 0xffff8000, v6
	v_lshl_add_u32 v1, v1, 11, v6
	v_and_b32_e32 v0, 1, v0
	v_lshl_or_b32 v0, v0, 6, v1
	v_lshl_add_u32 v134, v2, 1, v0
	v_lshlrev_b32_e32 v0, 14, v3
	v_and_b32_e32 v0, 0xffff8000, v0
	v_lshl_add_u32 v0, v4, 11, v0
	v_and_b32_e32 v1, 1, v3
	s_waitcnt vmcnt(6)
	v_lshl_or_b32 v0, v1, 6, v0
	v_lshl_add_u32 v136, v5, 1, v0
	v_mov_b32_e32 v0, 0
	v_mov_b32_e32 v135, v197
	v_mov_b32_e32 v137, v197
	s_mov_b32 s24, 0
	v_add_u32_e32 v144, 0, v16
	v_mov_b32_e32 v1, v0
	v_mov_b32_e32 v2, v0
	v_mov_b32_e32 v3, v0
	v_mov_b32_e32 v4, v0
	v_mov_b32_e32 v5, v0
	v_mov_b32_e32 v6, v0
	v_mov_b32_e32 v7, v0
	v_mov_b32_e32 v16, v0
	v_mov_b32_e32 v17, v0
	v_mov_b32_e32 v18, v0
	v_mov_b32_e32 v19, v0
	v_mov_b32_e32 v20, v0
	v_mov_b32_e32 v21, v0
	v_mov_b32_e32 v22, v0
	v_mov_b32_e32 v23, v0
	v_mov_b32_e32 v32, v0
	v_mov_b32_e32 v33, v0
	v_mov_b32_e32 v34, v0
	v_mov_b32_e32 v35, v0
	v_mov_b32_e32 v36, v0
	v_mov_b32_e32 v37, v0
	v_mov_b32_e32 v38, v0
	v_mov_b32_e32 v39, v0
	v_mov_b32_e32 v48, v0
	v_mov_b32_e32 v49, v0
	v_mov_b32_e32 v50, v0
	v_mov_b32_e32 v51, v0
	v_mov_b32_e32 v52, v0
	v_mov_b32_e32 v53, v0
	v_mov_b32_e32 v54, v0
	v_mov_b32_e32 v55, v0
	v_mov_b32_e32 v8, v0
	v_mov_b32_e32 v9, v0
	v_mov_b32_e32 v10, v0
	v_mov_b32_e32 v11, v0
	v_mov_b32_e32 v12, v0
	v_mov_b32_e32 v13, v0
	v_mov_b32_e32 v14, v0
	v_mov_b32_e32 v15, v0
	v_mov_b32_e32 v24, v0
	v_mov_b32_e32 v25, v0
	v_mov_b32_e32 v26, v0
	v_mov_b32_e32 v27, v0
	v_mov_b32_e32 v28, v0
	v_mov_b32_e32 v29, v0
	v_mov_b32_e32 v30, v0
	v_mov_b32_e32 v31, v0
	v_mov_b32_e32 v40, v0
	v_mov_b32_e32 v41, v0
	v_mov_b32_e32 v42, v0
	v_mov_b32_e32 v43, v0
	v_mov_b32_e32 v44, v0
	v_mov_b32_e32 v45, v0
	v_mov_b32_e32 v46, v0
	v_mov_b32_e32 v47, v0
	v_mov_b32_e32 v56, v0
	v_mov_b32_e32 v57, v0
	v_mov_b32_e32 v58, v0
	v_mov_b32_e32 v59, v0
	v_mov_b32_e32 v60, v0
	v_mov_b32_e32 v61, v0
	v_mov_b32_e32 v62, v0
	v_mov_b32_e32 v63, v0
	v_mov_b32_e32 v64, v0
	v_mov_b32_e32 v65, v0
	v_mov_b32_e32 v66, v0
	v_mov_b32_e32 v67, v0
	v_mov_b32_e32 v68, v0
	v_mov_b32_e32 v69, v0
	v_mov_b32_e32 v70, v0
	v_mov_b32_e32 v71, v0
	v_mov_b32_e32 v80, v0
	v_mov_b32_e32 v81, v0
	v_mov_b32_e32 v82, v0
	v_mov_b32_e32 v83, v0
	v_mov_b32_e32 v84, v0
	v_mov_b32_e32 v85, v0
	v_mov_b32_e32 v86, v0
	v_mov_b32_e32 v87, v0
	v_mov_b32_e32 v96, v0
	v_mov_b32_e32 v97, v0
	v_mov_b32_e32 v98, v0
	v_mov_b32_e32 v99, v0
	v_mov_b32_e32 v100, v0
	v_mov_b32_e32 v101, v0
	v_mov_b32_e32 v102, v0
	v_mov_b32_e32 v103, v0
	v_mov_b32_e32 v112, v0
	v_mov_b32_e32 v113, v0
	v_mov_b32_e32 v114, v0
	v_mov_b32_e32 v115, v0
	v_mov_b32_e32 v116, v0
	v_mov_b32_e32 v117, v0
	v_mov_b32_e32 v118, v0
	v_mov_b32_e32 v119, v0
	v_mov_b32_e32 v72, v0
	v_mov_b32_e32 v73, v0
	v_mov_b32_e32 v74, v0
	v_mov_b32_e32 v75, v0
	v_mov_b32_e32 v76, v0
	v_mov_b32_e32 v77, v0
	v_mov_b32_e32 v78, v0
	v_mov_b32_e32 v79, v0
	v_mov_b32_e32 v88, v0
	v_mov_b32_e32 v89, v0
	v_mov_b32_e32 v90, v0
	v_mov_b32_e32 v91, v0
	v_mov_b32_e32 v92, v0
	v_mov_b32_e32 v93, v0
	v_mov_b32_e32 v94, v0
	v_mov_b32_e32 v95, v0
	v_mov_b32_e32 v104, v0
	v_mov_b32_e32 v105, v0
	v_mov_b32_e32 v106, v0
	v_mov_b32_e32 v107, v0
	v_mov_b32_e32 v108, v0
	v_mov_b32_e32 v109, v0
	v_mov_b32_e32 v110, v0
	v_mov_b32_e32 v111, v0
	v_mov_b32_e32 v120, v0
	v_mov_b32_e32 v121, v0
	v_mov_b32_e32 v122, v0
	v_mov_b32_e32 v123, v0
	v_mov_b32_e32 v124, v0
	v_mov_b32_e32 v125, v0
	v_mov_b32_e32 v126, v0
	v_mov_b32_e32 v127, v0
	s_barrier

.LBB0_1025:
	v_lshl_add_u64 v[6:7], s[48:49], 0, v[196:197]
	v_mov_b32_e32 v133, v197
	v_and_b32_e32 v143, 15, v142
	v_and_b32_e32 v14, 48, v142
	v_lshlrev_b32_e32 v15, 2, v142
	v_lshl_add_u64 v[8:9], s[48:49], 0, v[132:133]
	v_mov_b32_e32 v129, v197
	s_sext_i32_i8 s8, s4
	s_and_b32 s3, s1, 3
	s_lshl_b32 s4, s18, 6
	s_lshl_b32 s18, s18, 13
	v_lshl_or_b32 v14, v143, 6, v14
	v_and_b32_e32 v15, 32, v15
	s_add_i32 m0, s7, 0x18000
	v_lshl_add_u64 v[6:7], v[6:7], 0, s[10:11]
	v_lshl_add_u64 v[10:11], s[12:13], 0, v[128:129]
	v_mov_b32_e32 v131, v197
	v_bitop3_b32 v16, v14, s18, v15 bitop3:0xde
	s_lshl_b32 s18, s3, 12
	global_load_lds_dwordx4 v[6:7], off
	v_lshl_add_u64 v[6:7], v[8:9], 0, s[10:11]
	s_add_i32 m0, s7, 0x1a000
	s_add_i32 s23, s7, 0x8000
	s_add_i32 s24, s7, 0xa000
	v_lshl_add_u64 v[12:13], s[12:13], 0, v[130:131]
	v_bitop3_b32 v144, v14, s18, v15 bitop3:0xde
	global_load_lds_dwordx4 v[6:7], off
	v_lshl_add_u64 v[6:7], v[10:11], 0, s[10:11]
	s_mov_b32 m0, s23
	s_add_u32 s18, s48, 0x40080
	global_load_lds_dwordx4 v[6:7], off
	v_lshl_add_u64 v[6:7], v[12:13], 0, s[10:11]
	s_mov_b32 m0, s24
	s_addc_u32 s19, s49, 0
	global_load_lds_dwordx4 v[6:7], off
	s_add_i32 m0, s7, 0x1c000
	v_lshl_add_u64 v[6:7], s[18:19], 0, v[196:197]
	global_load_lds_dwordx4 v[6:7], off
	v_lshl_add_u64 v[6:7], s[18:19], 0, v[132:133]
	s_add_i32 m0, s7, 0x1e000
	v_or_b32_e32 v146, s4, v143
	global_load_lds_dwordx4 v[6:7], off
	s_waitcnt vmcnt(8)
	s_barrier
	v_lshlrev_b32_e32 v6, 14, v0
	v_and_b32_e32 v6, 0xffff8000, v6
	v_lshl_add_u32 v1, v1, 11, v6
	v_and_b32_e32 v0, 1, v0
	v_lshl_or_b32 v0, v0, 6, v1
	v_lshl_add_u32 v134, v2, 1, v0
	v_lshlrev_b32_e32 v0, 14, v3
	v_and_b32_e32 v0, 0xffff8000, v0
	v_lshl_add_u32 v0, v4, 11, v0
	v_and_b32_e32 v1, 1, v3
	s_waitcnt vmcnt(6)
	v_lshl_or_b32 v0, v1, 6, v0
	v_lshl_add_u32 v136, v5, 1, v0
	v_mov_b32_e32 v0, 0
	v_mov_b32_e32 v135, v197
	v_mov_b32_e32 v137, v197
	s_mov_b32 s25, 0
	v_add_u32_e32 v145, 0, v16
	v_mov_b32_e32 v1, v0
	v_mov_b32_e32 v2, v0
	v_mov_b32_e32 v3, v0
	v_mov_b32_e32 v4, v0
	v_mov_b32_e32 v5, v0
	v_mov_b32_e32 v6, v0
	v_mov_b32_e32 v7, v0
	v_mov_b32_e32 v16, v0
	v_mov_b32_e32 v17, v0
	v_mov_b32_e32 v18, v0
	v_mov_b32_e32 v19, v0
	v_mov_b32_e32 v20, v0
	v_mov_b32_e32 v21, v0
	v_mov_b32_e32 v22, v0
	v_mov_b32_e32 v23, v0
	v_mov_b32_e32 v32, v0
	v_mov_b32_e32 v33, v0
	v_mov_b32_e32 v34, v0
	v_mov_b32_e32 v35, v0
	v_mov_b32_e32 v36, v0
	v_mov_b32_e32 v37, v0
	v_mov_b32_e32 v38, v0
	v_mov_b32_e32 v39, v0
	v_mov_b32_e32 v48, v0
	v_mov_b32_e32 v49, v0
	v_mov_b32_e32 v50, v0
	v_mov_b32_e32 v51, v0
	v_mov_b32_e32 v52, v0
	v_mov_b32_e32 v53, v0
	v_mov_b32_e32 v54, v0
	v_mov_b32_e32 v55, v0
	v_mov_b32_e32 v8, v0
	v_mov_b32_e32 v9, v0
	v_mov_b32_e32 v10, v0
	v_mov_b32_e32 v11, v0
	v_mov_b32_e32 v12, v0
	v_mov_b32_e32 v13, v0
	v_mov_b32_e32 v14, v0
	v_mov_b32_e32 v15, v0
	v_mov_b32_e32 v24, v0
	v_mov_b32_e32 v25, v0
	v_mov_b32_e32 v26, v0
	v_mov_b32_e32 v27, v0
	v_mov_b32_e32 v28, v0
	v_mov_b32_e32 v29, v0
	v_mov_b32_e32 v30, v0
	v_mov_b32_e32 v31, v0
	v_mov_b32_e32 v40, v0
	v_mov_b32_e32 v41, v0
	v_mov_b32_e32 v42, v0
	v_mov_b32_e32 v43, v0
	v_mov_b32_e32 v44, v0
	v_mov_b32_e32 v45, v0
	v_mov_b32_e32 v46, v0
	v_mov_b32_e32 v47, v0
	v_mov_b32_e32 v56, v0
	v_mov_b32_e32 v57, v0
	v_mov_b32_e32 v58, v0
	v_mov_b32_e32 v59, v0
	v_mov_b32_e32 v60, v0
	v_mov_b32_e32 v61, v0
	v_mov_b32_e32 v62, v0
	v_mov_b32_e32 v63, v0
	v_mov_b32_e32 v64, v0
	v_mov_b32_e32 v65, v0
	v_mov_b32_e32 v66, v0
	v_mov_b32_e32 v67, v0
	v_mov_b32_e32 v68, v0
	v_mov_b32_e32 v69, v0
	v_mov_b32_e32 v70, v0
	v_mov_b32_e32 v71, v0
	v_mov_b32_e32 v80, v0
	v_mov_b32_e32 v81, v0
	v_mov_b32_e32 v82, v0
	v_mov_b32_e32 v83, v0
	v_mov_b32_e32 v100, v0
	v_mov_b32_e32 v101, v0
	v_mov_b32_e32 v102, v0
	v_mov_b32_e32 v103, v0
	v_mov_b32_e32 v120, v0
	v_mov_b32_e32 v121, v0
	v_mov_b32_e32 v122, v0
	v_mov_b32_e32 v123, v0
	v_mov_b32_e32 v124, v0
	v_mov_b32_e32 v125, v0
	v_mov_b32_e32 v126, v0
	v_mov_b32_e32 v127, v0
	v_mov_b32_e32 v92, v0
	v_mov_b32_e32 v93, v0
	v_mov_b32_e32 v94, v0
	v_mov_b32_e32 v95, v0
	v_mov_b32_e32 v96, v0
	v_mov_b32_e32 v97, v0
	v_mov_b32_e32 v98, v0
	v_mov_b32_e32 v99, v0
	v_mov_b32_e32 v104, v0
	v_mov_b32_e32 v105, v0
	v_mov_b32_e32 v106, v0
	v_mov_b32_e32 v107, v0
	v_mov_b32_e32 v108, v0
	v_mov_b32_e32 v109, v0
	v_mov_b32_e32 v110, v0
	v_mov_b32_e32 v111, v0
	v_mov_b32_e32 v84, v0
	v_mov_b32_e32 v85, v0
	v_mov_b32_e32 v86, v0
	v_mov_b32_e32 v87, v0
	v_mov_b32_e32 v88, v0
	v_mov_b32_e32 v89, v0
	v_mov_b32_e32 v90, v0
	v_mov_b32_e32 v91, v0
	v_mov_b32_e32 v112, v0
	v_mov_b32_e32 v113, v0
	v_mov_b32_e32 v114, v0
	v_mov_b32_e32 v115, v0
	v_mov_b32_e32 v116, v0
	v_mov_b32_e32 v117, v0
	v_mov_b32_e32 v118, v0
	v_mov_b32_e32 v119, v0
	v_mov_b32_e32 v72, v0
	v_mov_b32_e32 v73, v0
	v_mov_b32_e32 v74, v0
	v_mov_b32_e32 v75, v0
	v_mov_b32_e32 v76, v0
	v_mov_b32_e32 v77, v0
	v_mov_b32_e32 v78, v0
	v_mov_b32_e32 v79, v0
	s_barrier
